# C + GEMM K-loop heads at phase 0 mod 64 + attention loop head and indexer scoring loop heads also padded to phase 0 (code placement)
# speedup vs baseline: 1.0025x; 1.0025x over previous
; #define LAS __attribute__((address_space(3)))
; __device__ __forceinline__ void idx_scores8(const Params& p, LAS unsigned char* buf, int b, int c, int s8, int pw, int lane, int nw) {
;     ...
;     if (c < 4) return;
;     const int S = 64 * (c + 1); const size_t rowbase = (size_t)b * SEQ; const size_t q0 = rowbase + c * 64 + s8 * 8;
;     const int NVH = (c + 2) >> 1, SP = 64 * NVH;
;     const int r = lane & 31, h = lane >> 5;
;     const int hh = (r >> 2) & 1, reg = (r & 3) + 4 * (r >> 3), ql = (reg >> 3) + 2 * hh, head = reg & 7;
;     bf16x8 af[2][4]; hp2_t wv[2][2][4];
; #pragma unroll
;     for (int rb = 0; rb < 2; ++rb) { const bf16* src = proj + (q0 + rb * 4 + ql) * NPROJ + PC_QI + head * 64 + 32 * h;
; #pragma unroll
;         for (int s = 0; s < 4; ++s) af[rb][s] = *(const bf16x8*)(src + 8 * s);
; #pragma unroll
;         for (int e = 0; e < 2; ++e) { const float* wsrc = wis + (q0 + rb * 4 + 2 * h + e) * 8; const f32x4 w0 = *(const f32x4*)wsrc, w1 = *(const f32x4*)(wsrc + 4);
; #pragma unroll
;             for (int i = 0; i < 2; ++i) { wv[rb][e][i] = (hp2_t){(_Float16)w0[2 * i], (_Float16)w0[2 * i + 1]}; wv[rb][e][2 + i] = (hp2_t){(_Float16)w1[2 * i], (_Float16)w1[2 * i + 1]}; } } }
;     const int nct = S / 32;
;     const bf16* kbase = kir + rowbase * 64 + (4 * h * 32 + r) * 8;
;     LAS unsigned char* rowq = buf + (2 * h) * 8192;
;     bf16x8 bcur[4];
; #pragma unroll
;     for (int s = 0; s < 4; ++s) bcur[s] = *(const bf16x8*)(kbase + (size_t)pw * 2048 + 256 * s);
.LBB0_3687:
	s_and_b64 vcc, exec, s[0:1]
	s_cbranch_vccz .LBB0_3693
	s_cmp_eq_u32 s84, 16
	s_cbranch_scc1 .LBB0_3693
	s_cmp_lt_u32 s84, 8
	s_cselect_b32 s1, s40, s46
	s_cmp_lt_u32 s1, 4
	s_cbranch_scc1 .LBB0_3693
	s_lshl_b32 s0, s1, 5
	s_add_i32 s4, s0, 64
	s_add_i32 s0, s4, s0
	s_lshr_b32 s0, s0, 5
	v_readlane_b32 s6, v242, 51
	s_cmp_ge_u32 s6, s0
	v_readlane_b32 s7, v242, 52
	s_cbranch_scc1 .LBB0_3693
	s_lshl_b32 s5, s84, 3
	s_lshl_b32 s1, s1, 6
	s_and_b32 s5, s5, 56
	s_or_b32 s1, s1, s5
	v_readlane_b32 s12, v241, 23
	s_or_b32 s6, s12, s1
	v_or_b32_e32 v0, s6, v80
	s_waitcnt vmcnt(0)
	v_mov_b64_e32 v[16:17], s[82:83]
	s_movk_i32 s7, 0x2a00
	v_readlane_b32 s13, v241, 24
	s_and_b32 s1, s4, 0xfc0
	v_mad_u64_u32 v[0:1], s[4:5], v0, s7, v[16:17]
	v_mad_i32_i24 v1, s13, v114, v1
	v_lshl_add_u64 v[0:1], v[0:1], 0, v[78:79]
	v_mov_b32_e32 v89, v79
	v_lshl_add_u64 v[0:1], v[0:1], 0, v[88:89]
	s_mov_b64 s[14:15], 0x2001400
	s_mov_b32 s12, 0x2001000
	v_lshl_add_u64 v[2:3], v[0:1], 0, s[14:15]
	v_add_co_u32_e32 v0, vcc, s12, v0
	v_readlane_b32 s10, v242, 55
	s_nop 0
	v_addc_co_u32_e32 v1, vcc, 0, v1, vcc
	global_load_dwordx4 v[32:35], v[0:1], off offset:1024
	global_load_dwordx4 v[36:39], v[2:3], off offset:16
	global_load_dwordx4 v[40:43], v[2:3], off offset:32
	global_load_dwordx4 v[44:47], v[2:3], off offset:48
	v_mov_b32_e32 v1, s13
	v_or_b32_e32 v0, s6, v82
	v_lshlrev_b64 v[0:1], 5, v[0:1]
	v_readlane_b32 s11, v242, 56
	s_or_b32 s6, s6, 4
	s_nop 0
	v_lshl_add_u64 v[12:13], s[10:11], 0, v[0:1]
	global_load_dwordx4 v[0:3], v[12:13], off offset:48
	global_load_dwordx4 v[4:7], v[12:13], off offset:32
	global_load_dwordx4 v[8:11], v[12:13], off offset:16
	s_nop 0
	global_load_dwordx4 v[12:15], v[12:13], off
	v_or_b32_e32 v160, s6, v80
	v_mad_u64_u32 v[160:161], s[4:5], v160, s7, v[16:17]
	v_mad_i32_i24 v161, s13, v114, v161
	v_lshl_add_u64 v[160:161], v[160:161], 0, v[78:79]
	v_lshl_add_u64 v[160:161], v[160:161], 0, v[88:89]
	v_lshl_add_u64 v[162:163], v[160:161], 0, s[14:15]
	v_add_co_u32_e32 v160, vcc, s12, v160
	s_nop 1
	v_addc_co_u32_e32 v161, vcc, 0, v161, vcc
	global_load_dwordx4 v[48:51], v[160:161], off offset:1024
	global_load_dwordx4 v[52:55], v[162:163], off offset:16
	global_load_dwordx4 v[56:59], v[162:163], off offset:32
	global_load_dwordx4 v[60:63], v[162:163], off offset:48
	v_mov_b32_e32 v161, s13
	v_or_b32_e32 v160, s6, v82
	v_lshlrev_b64 v[160:161], 5, v[160:161]
	v_lshl_add_u64 v[164:165], s[10:11], 0, v[160:161]
	global_load_dwordx4 v[144:147], v[164:165], off offset:48
	global_load_dwordx4 v[148:151], v[164:165], off offset:32
	global_load_dwordx4 v[152:155], v[164:165], off offset:16
	global_load_dwordx4 v[156:159], v[164:165], off
	global_load_dwordx4 v[64:67], v[94:95], off offset:1536
	global_load_dwordx4 v[68:71], v[94:95], off offset:1024
	global_load_dwordx4 v[72:75], v[94:95], off offset:512
	global_load_dwordx4 v[16:19], v[94:95], off
	v_readlane_b32 s6, v242, 51
	v_readlane_b32 s4, v242, 58
	s_mov_b32 s5, s6
	v_readlane_b32 s7, v242, 52
	s_waitcnt vmcnt(12)
	v_cvt_pk_f16_f32 v121, v0, v1
	v_cvt_pk_f16_f32 v123, v2, v3
	v_cvt_pk_f16_f32 v116, v12, v13
	v_cvt_pk_f16_f32 v117, v8, v9
	v_cvt_pk_f16_f32 v118, v14, v15
	v_cvt_pk_f16_f32 v119, v10, v11
	v_cvt_pk_f16_f32 v120, v4, v5
	v_cvt_pk_f16_f32 v122, v6, v7
	s_waitcnt vmcnt(4)
	v_cvt_pk_f16_f32 v128, v144, v145
	v_cvt_pk_f16_f32 v124, v152, v153
	v_cvt_pk_f16_f32 v89, v156, v157
	v_cvt_pk_f16_f32 v125, v158, v159
	v_cvt_pk_f16_f32 v126, v154, v155
	v_cvt_pk_f16_f32 v127, v148, v149
	v_cvt_pk_f16_f32 v129, v150, v151
	v_cvt_pk_f16_f32 v130, v146, v147
	v_cndmask_b32_e64 v0, 0, 1, s[2:3]
	s_nop 0
	v_lshl_add_u32 v131, v0, 16, v112
	s_nop 0
	s_nop 0
	s_nop 0
	s_nop 0
	s_nop 0
	s_nop 0
	s_nop 0
	s_nop 0
	s_nop 0
	s_nop 0
	s_nop 0
	s_nop 0
	s_nop 0
	s_nop 0

; #define LAS __attribute__((address_space(3)))
; __device__ __forceinline__ void idx_scores8(const Params& p, LAS unsigned char* buf, int b, int c, int s8, int pw, int lane, int nw) {
;     ...
;     for (int rb = 0; rb < 2; ++rb) { const bf16* src = proj + (q0 + rb * 4 + ql) * NPROJ + PC_QI + head * 64 + 32 * h;
; #pragma unroll
;         for (int s = 0; s < 4; ++s) af[rb][s] = *(const bf16x8*)(src + 8 * s);
; #pragma unroll
;         for (int e = 0; e < 2; ++e) { const float* wsrc = wis + (q0 + rb * 4 + 2 * h + e) * 8; const f32x4 w0 = *(const f32x4*)wsrc, w1 = *(const f32x4*)(wsrc + 4);
; #pragma unroll
;             for (int i = 0; i < 2; ++i) { wv[rb][e][i] = (hp2_t){(_Float16)w0[2 * i], (_Float16)w0[2 * i + 1]}; wv[rb][e][2 + i] = (hp2_t){(_Float16)w1[2 * i], (_Float16)w1[2 * i + 1]}; } } }
;     const int nct = S / 32;
;     const bf16* kbase = kir + rowbase * 64 + (4 * h * 32 + r) * 8;
;     LAS unsigned char* rowq = buf + (2 * h) * 8192;
;     bf16x8 bcur[4];
; #pragma unroll
;     for (int s = 0; s < 4; ++s) bcur[s] = *(const bf16x8*)(kbase + (size_t)pw * 2048 + 256 * s);
.LBB0_3694:
	s_andn2_b64 vcc, exec, s[0:1]
	s_cbranch_vccnz .LBB0_601
	s_andn2_b64 vcc, exec, s[66:67]
	s_cbranch_vccnz .LBB0_601
	global_load_dwordx4 v[32:35], v[96:97], off
	global_load_dwordx4 v[36:39], v[96:97], off offset:16
	global_load_dwordx4 v[40:43], v[96:97], off offset:32
	global_load_dwordx4 v[44:47], v[96:97], off offset:48
	global_load_dwordx4 v[0:3], v[98:99], off offset:48
	global_load_dwordx4 v[4:7], v[98:99], off offset:32
	global_load_dwordx4 v[8:11], v[98:99], off offset:16
	global_load_dwordx4 v[12:15], v[98:99], off
	v_mov_b32_e32 v131, v113
	s_mov_b32 s0, s97
	s_mov_b32 s1, s44
	s_waitcnt vmcnt(3)
	v_cvt_pk_f16_f32 v120, v0, v1
	s_waitcnt vmcnt(2)
	v_cvt_pk_f16_f32 v119, v4, v5
	s_waitcnt vmcnt(1)
	v_cvt_pk_f16_f32 v116, v8, v9
	s_waitcnt vmcnt(0)
	v_cvt_pk_f16_f32 v89, v12, v13
	v_cvt_pk_f16_f32 v117, v14, v15
	v_cvt_pk_f16_f32 v118, v10, v11
	v_cvt_pk_f16_f32 v121, v6, v7
	v_cvt_pk_f16_f32 v122, v2, v3
	global_load_dwordx4 v[48:51], v[100:101], off
	global_load_dwordx4 v[52:55], v[100:101], off offset:16
	global_load_dwordx4 v[56:59], v[100:101], off offset:32
	global_load_dwordx4 v[60:63], v[100:101], off offset:48
	global_load_dwordx4 v[0:3], v[102:103], off offset:48
	global_load_dwordx4 v[4:7], v[102:103], off offset:32
	global_load_dwordx4 v[8:11], v[102:103], off offset:16
	global_load_dwordx4 v[12:15], v[102:103], off
	global_load_dwordx4 v[64:67], v[104:105], off offset:1536
	global_load_dwordx4 v[68:71], v[104:105], off offset:1024
	global_load_dwordx4 v[72:75], v[104:105], off offset:512
	global_load_dwordx4 v[16:19], v[104:105], off
	s_waitcnt vmcnt(7)
	v_cvt_pk_f16_f32 v128, v0, v1
	s_waitcnt vmcnt(6)
	v_cvt_pk_f16_f32 v127, v4, v5
	s_waitcnt vmcnt(5)
	v_cvt_pk_f16_f32 v124, v8, v9
	s_waitcnt vmcnt(4)
	v_cvt_pk_f16_f32 v123, v12, v13
	v_cvt_pk_f16_f32 v125, v14, v15
	v_cvt_pk_f16_f32 v126, v10, v11
	v_cvt_pk_f16_f32 v129, v6, v7
	v_cvt_pk_f16_f32 v130, v2, v3
	s_nop 0
	s_nop 0
	s_nop 0
	s_nop 0
	s_nop 0
	s_nop 0
	s_nop 0
	s_nop 0
	s_nop 0
	s_nop 0
	s_nop 0
	s_nop 0
	s_nop 0
	s_nop 0
	s_nop 0

; #define LAS __attribute__((address_space(3)))
; __device__ __forceinline__ void attn_unit(const Params& p, LAS unsigned char* lds, int b, int h, int qb, int tid, int wid, int lane, u64& tacc, v4u& kA, v4u& vA, v4u& kB, v4u& vB, const bool first) {
;     ...
;     const u64* bmq = bm + (rowbase + q0 + wid * 32 + r32) * 64;
;     const unsigned stoff = wid * 1024 + lane * 16;
;     const unsigned vboff = 8192 + ((lane >> 4) & 1) * 32 + (lane & 3) * 8 + (4 * hi + ((lane & 15) >> 2)) * 64;
;     float m = 0.f; bool started = false; f32x16 o0, o1, o2;
; #pragma unroll
;     for (int i = 0; i < 16; ++i) { o0[i] = 0.f; o1[i] = 0.f; o2[i] = 0.f; }
;     float negv = -1e30f; asm volatile("" : "+v"(negv));
;     const bf16x8 ones8 = (bf16x8){0x3f80, 0x3f80, 0x3f80, 0x3f80, 0x3f80, 0x3f80, 0x3f80, 0x3f80};
;     v4u mwc = *(const v4u*)bmq, mwn = mwc;
;     if (first) {
;         kB = *(const v4u*)ksrc; vB = *(const v4u*)vsrc;
;         kA = *(const v4u*)(ksrc + (size_t)4096); vA = *(const v4u*)(vsrc + (size_t)4096);
;         *(LAS v4u*)(lds + stoff) = kB; *(LAS v4u*)(lds + 8192 + stoff) = vB;
;         kB = *(const v4u*)(ksrc + (size_t)2 * 4096); vB = *(const v4u*)(vsrc + (size_t)2 * 4096);
;     }
;     bf16x8 Eop[2];
; #pragma unroll
;     for (int s = 0; s < 2; ++s) { v4u e; unsigned* ep = (unsigned*)&e;
; #pragma unroll
;         for (int i = 0; i < 4; ++i) { const int k0 = 4 * s + i + 8 * hi; ep[i] = (r32 == k0 ? 0x3F80u : 0u) | (r32 == k0 + 16 ? 0x3F800000u : 0u); }
;         Eop[s] = __builtin_bit_cast(bf16x8, e); }
;     f32x16 nsplat;
; #pragma unroll
;     for (int r = 0; r < 16; ++r) nsplat[r] = -m;
.LBB0_3758:
	v_lshl_add_u64 v[2:3], v[194:195], 0, s[2:3]
	v_lshlrev_b64 v[2:3], 9, v[2:3]
	s_waitcnt vmcnt(5)
	v_mov_b32_e32 v14, v0
	v_mov_b32_e32 v15, v0
	v_lshl_add_u64 v[196:197], s[6:7], 0, v[2:3]
	v_mov_b32_e32 v1, v0
	v_mov_b32_e32 v2, v0
	v_mov_b32_e32 v3, v0
	v_mov_b32_e32 v4, v0
	v_mov_b32_e32 v5, v0
	v_mov_b32_e32 v6, v0
	v_mov_b32_e32 v7, v0
	v_mov_b32_e32 v8, v0
	v_mov_b32_e32 v9, v0
	v_mov_b32_e32 v10, v0
	v_mov_b32_e32 v11, v0
	v_mov_b32_e32 v12, v0
	v_mov_b32_e32 v13, v0
	v_mov_b32_e32 v30, v159
	v_mov_b32_e32 v31, v159
	v_mov_b64_e32 v[78:79], v[14:15]
	s_lshl_b32 s46, s0, 2
	v_mov_b32_e32 v16, v159
	v_mov_b32_e32 v17, v159
	v_mov_b32_e32 v18, v159
	v_mov_b32_e32 v19, v159
	v_mov_b32_e32 v20, v159
	v_mov_b32_e32 v21, v159
	v_mov_b32_e32 v22, v159
	v_mov_b32_e32 v23, v159
	v_mov_b32_e32 v24, v159
	v_mov_b32_e32 v25, v159
	v_mov_b32_e32 v26, v159
	v_mov_b32_e32 v27, v159
	v_mov_b32_e32 v28, v159
	v_mov_b32_e32 v29, v159
	v_mov_b64_e32 v[46:47], v[30:31]
	v_mov_b64_e32 v[62:63], v[30:31]
	v_mov_b64_e32 v[76:77], v[12:13]
	v_mov_b64_e32 v[74:75], v[10:11]
	v_mov_b64_e32 v[72:73], v[8:9]
	v_mov_b64_e32 v[70:71], v[6:7]
	v_mov_b64_e32 v[68:69], v[4:5]
	v_mov_b64_e32 v[66:67], v[2:3]
	v_mov_b64_e32 v[64:65], v[0:1]
	s_waitcnt vmcnt(0)
	v_mov_b64_e32 v[2:3], v[152:153]
	s_add_i32 s47, s46, s25
	s_add_i32 s48, s46, 4
	s_mov_b32 s51, 0
	s_sub_i32 s49, 0, s46
	s_mov_b64 s[20:21], 0
	v_mov_b32_e32 v171, 0
	v_mov_b64_e32 v[44:45], v[28:29]
	v_mov_b64_e32 v[42:43], v[26:27]
	v_mov_b64_e32 v[40:41], v[24:25]
	v_mov_b64_e32 v[38:39], v[22:23]
	v_mov_b64_e32 v[36:37], v[20:21]
	v_mov_b64_e32 v[34:35], v[18:19]
	v_mov_b64_e32 v[32:33], v[16:17]
	v_mov_b64_e32 v[60:61], v[28:29]
	v_mov_b64_e32 v[58:59], v[26:27]
	v_mov_b64_e32 v[56:57], v[24:25]
	v_mov_b64_e32 v[54:55], v[22:23]
	v_mov_b64_e32 v[52:53], v[20:21]
	v_mov_b64_e32 v[50:51], v[18:19]
	v_mov_b64_e32 v[48:49], v[16:17]
	v_mov_b64_e32 v[4:5], v[154:155]
	s_nop 0
	s_nop 0

;     __device__ bool next(int i, Unit& u) const { if (i != 0) return false; return so.next(round, u); }
;     __device__ __forceinline__ bool next(int i, Unit& u) const { if (i > 0 || !on) return false; u.pm = pm; u.pn = 0; return true; }
; template <class Epi, class Sched, bool ALIGN_EPI = false, bool SP2 = false, bool MIDHOOK = false>
; __device__ __forceinline__ void gemm_phase(PG8_LAS unsigned char* lds, const Gemm g, const Sched& S, const Epi& E) {
;     ...
;         const bool has_next = S.next(ui + 1, nxt);
;         const char* nA = has_next ? (const char*)g.A + (size_t)nxt.pm * tstep : cA; const char* nB = has_next ? (const char*)g.Bt + (size_t)nxt.pn * tstep : cB;
;     ...
; #pragma unroll
;         for (int a = 0; a < 2; ++a)
; #pragma unroll
;             for (int b = 0; b < 2; ++b)
; #pragma unroll
;                 for (int m = 0; m < 4; ++m)
; #pragma unroll
;                     for (int n = 0; n < 2; ++n) acc[a][b][m][n] = (f32x4){0.f, 0.f, 0.f, 0.f};
;         cur = nxt; cA = nA; cB = nB; ++ui;
.LBB0_3840:
	s_ashr_i32 s19, s18, 31
	s_lshl_b64 s[20:21], s[18:19], 19
	s_add_u32 s20, s68, s20
	s_addc_u32 s21, s69, s21
	s_and_b64 s[22:23], s[0:1], exec
	s_cselect_b32 s19, s21, s25
	s_cselect_b32 s46, s20, s24
	s_ashr_i32 s17, s16, 31
	s_lshl_b64 s[22:23], s[16:17], 19
	v_readlane_b32 s30, v243, 24
	v_readlane_b32 s31, v243, 25
	s_add_u32 s22, s30, s22
	s_addc_u32 s23, s31, s23
	s_and_b64 s[30:31], s[0:1], exec
	v_mov_b32_e32 v2, v0
	v_mov_b32_e32 v3, v0
	s_cselect_b32 s17, s23, s29
	s_cselect_b32 s47, s22, s28
	s_add_u32 s48, s28, 0x100
	v_mov_b32_e32 v1, v0
	v_mov_b64_e32 v[6:7], v[2:3]
	v_mov_b64_e32 v[10:11], v[2:3]
	v_mov_b64_e32 v[22:23], v[2:3]
	v_mov_b64_e32 v[26:27], v[2:3]
	v_mov_b64_e32 v[38:39], v[2:3]
	v_mov_b64_e32 v[42:43], v[2:3]
	v_mov_b64_e32 v[54:55], v[2:3]
	v_mov_b64_e32 v[58:59], v[2:3]
	v_mov_b64_e32 v[14:15], v[2:3]
	v_mov_b64_e32 v[18:19], v[2:3]
	v_mov_b64_e32 v[30:31], v[2:3]
	v_mov_b64_e32 v[34:35], v[2:3]
	v_mov_b64_e32 v[46:47], v[2:3]
	v_mov_b64_e32 v[50:51], v[2:3]
	v_mov_b64_e32 v[62:63], v[2:3]
	v_mov_b64_e32 v[66:67], v[2:3]
	v_mov_b64_e32 v[70:71], v[2:3]
	v_mov_b64_e32 v[74:75], v[2:3]
	v_mov_b64_e32 v[86:87], v[2:3]
	v_mov_b64_e32 v[90:91], v[2:3]
	v_mov_b64_e32 v[102:103], v[2:3]
	v_mov_b64_e32 v[106:107], v[2:3]
	v_mov_b64_e32 v[118:119], v[2:3]
	v_mov_b64_e32 v[122:123], v[2:3]
	v_mov_b64_e32 v[78:79], v[2:3]
	v_mov_b64_e32 v[82:83], v[2:3]
	v_mov_b64_e32 v[94:95], v[2:3]
	v_mov_b64_e32 v[98:99], v[2:3]
	v_mov_b64_e32 v[110:111], v[2:3]
	v_mov_b64_e32 v[114:115], v[2:3]
	v_mov_b64_e32 v[126:127], v[2:3]
	v_mov_b64_e32 v[130:131], v[2:3]
	v_lshl_add_u32 v204, s26, 8, v223
	v_lshl_add_u32 v206, s27, 8, v225
	v_lshl_add_u64 v[208:209], s[24:25], 0, v[196:197]
	v_lshl_add_u64 v[210:211], s[24:25], 0, v[198:199]
	s_addc_u32 s49, s29, 0
	s_mov_b32 s50, -2
	s_mov_b64 s[26:27], 0
	v_mov_b64_e32 v[4:5], v[0:1]
	v_mov_b64_e32 v[8:9], v[0:1]
	v_mov_b64_e32 v[20:21], v[0:1]
	v_mov_b64_e32 v[24:25], v[0:1]
	v_mov_b64_e32 v[36:37], v[0:1]
	v_mov_b64_e32 v[40:41], v[0:1]
	v_mov_b64_e32 v[52:53], v[0:1]
	v_mov_b64_e32 v[56:57], v[0:1]
	v_mov_b64_e32 v[12:13], v[0:1]
	v_mov_b64_e32 v[16:17], v[0:1]
	v_mov_b64_e32 v[28:29], v[0:1]
	v_mov_b64_e32 v[32:33], v[0:1]
	v_mov_b64_e32 v[44:45], v[0:1]
	v_mov_b64_e32 v[48:49], v[0:1]
	v_mov_b64_e32 v[60:61], v[0:1]
	v_mov_b64_e32 v[64:65], v[0:1]
	v_mov_b64_e32 v[68:69], v[0:1]
	v_mov_b64_e32 v[72:73], v[0:1]
	v_mov_b64_e32 v[84:85], v[0:1]
	v_mov_b64_e32 v[88:89], v[0:1]
	v_mov_b64_e32 v[100:101], v[0:1]
	v_mov_b64_e32 v[104:105], v[0:1]
	v_mov_b64_e32 v[116:117], v[0:1]
	v_mov_b64_e32 v[120:121], v[0:1]
	v_mov_b64_e32 v[76:77], v[0:1]
	v_mov_b64_e32 v[80:81], v[0:1]
	v_mov_b64_e32 v[92:93], v[0:1]
	v_mov_b64_e32 v[96:97], v[0:1]
	v_mov_b64_e32 v[108:109], v[0:1]
	v_mov_b64_e32 v[112:113], v[0:1]
	v_mov_b64_e32 v[124:125], v[0:1]
	v_mov_b64_e32 v[128:129], v[0:1]
	s_branch .LBB0_3842
	s_nop 0
	s_nop 0
	s_nop 0
	s_nop 0
	s_nop 0
	s_nop 0
	s_nop 0
